# hand-written even-layer banded attention units: scalar unit decode, distance LUT bias, K and V rows requested one pair ahead, V rows transposed through a wave-private LDS tile
# speedup vs baseline: 1.2071x; 1.0152x over previous
.LBB0_1161:
	s_andn2_b64 vcc, exec, s[0:1]
	s_cbranch_vccnz .LBB0_1273
	v_readlane_b32 s2, v254, 5
	v_readlane_b32 s3, v254, 6
	v_mov_b32_e32 v0, v208
	v_readlane_b32 s5, v254, 0
	s_load_dwordx4 s[40:43], s[2:3], 0xa0
	s_load_dword s4, s[2:3], 0xb0
	s_and_b32 s6, s5, -8
	v_ashrrev_i32_e32 v1, 6, v0
	v_mul_lo_u32 v2, v1, s46
	v_add_u32_e32 v1, s6, v1
	v_readlane_b32 s6, v254, 14
	v_add_u32_e32 v2, s5, v2
	v_readlane_b32 s7, v254, 15
	s_waitcnt lgkmcnt(0)
	s_mov_b64 s[0:1], s[42:43]
	v_cndmask_b32_e64 v49, v2, v1, s[6:7]
	v_readlane_b32 s6, v254, 16
	s_nop 1
	v_cmp_gt_i32_e32 vcc, s6, v49
	s_and_saveexec_b64 s[30:31], vcc
	s_cbranch_execz .LBB0_1215
	s_cmpk_lg_i32 s46, 0x100
	s_cbranch_scc1 .Lband_orig
	s_load_dwordx2 s[6:7], s[2:3], 0x30
	v_readlane_b32 s8, v254, 33
	s_and_b32 s56, s5, 7
	s_lshl_b32 s8, s8, 3
	s_add_i32 s8, s8, s56
	s_lshl_b32 s8, s8, 2
	s_waitcnt lgkmcnt(0)
	s_load_dword s9, s[6:7], s8
	v_lshrrev_b32_e32 v0, 6, v208
	s_waitcnt lgkmcnt(0)
	v_readfirstlane_b32 s1, v0
	s_lshr_b32 s7, s5, 3
	s_lshl_b32 s7, s7, 3
	s_add_i32 s7, s7, s1
	s_lshl_b32 s48, s1, 10
	s_mov_b32 s40, 0x3e38aa3b
	s_mov_b32 s41, 0x3e38aa3b
	s_mov_b32 s57, 0x20400
	s_mul_i32 s0, s1, 0x1200
	s_add_i32 s0, s0, 0x2000
	v_and_b32_e32 v100, 63, v208
	v_lshrrev_b32_e32 v101, 3, v100
	v_mul_u32_u24_e32 v101, 0x90, v101
	v_and_b32_e32 v102, 7, v100
	v_lshl_add_u32 v101, v102, 4, v101
	v_add_u32_e32 v114, s0, v101
	v_bfe_u32 v101, v208, 4, 2
	v_mul_u32_u24_e32 v101, 0x240, v101
	v_and_b32_e32 v102, 15, v208
	v_lshl_add_u32 v101, v102, 1, v101
	v_add_u32_e32 v115, s0, v101
	v_and_b32_e32 v116, 15, v208
	v_bfe_u32 v100, v208, 4, 2
	v_lshlrev_b32_e32 v117, 2, v100
	v_lshlrev_b32_e32 v118, 3, v100
	v_cmp_eq_u32_e32 vcc, 0, v100
	s_nop 1
	v_cndmask_b32_e64 v120, 0, 1.0, vcc
	s_waitcnt lgkmcnt(0)
	v_mov_b32_e32 v119, s9
	v_mul_f32_e32 v119, 0x3fb8aa3b, v119
	s_mov_b32 s6, 0
	s_lshr_b32 s0, s6, 3
	s_cmp_eq_u32 s0, 0
	s_cselect_b32 s3, 1, 0
	s_add_i32 s1, s0, -1
	s_max_i32 s1, s1, 0
	s_lshl_b32 s13, s1, 1
	s_and_b32 s1, s6, 3
	s_lshl_b32 s1, s1, 8
	s_add_i32 s1, s1, s7
	s_sub_i32 s2, 10, s13
	s_lshr_b32 s14, s1, s2
	s_lshr_b32 s2, 0x400, s13
	s_add_i32 s2, s2, -1
	s_and_b32 s12, s1, s2
	s_lshl_b32 s8, s12, 4
	s_sub_i32 s2, 0x80, s3
	s_sub_i32 s2, s8, s2
	s_max_i32 s2, s2, 0
	s_lshr_b32 s2, s2, 4
	s_and_b32 s11, s2, -2
	s_sub_i32 s2, s12, s11
	s_lshr_b32 s2, s2, 1
	s_add_i32 s9, s2, 1
	s_bfe_u32 s2, s6, 0x10002
	s_mul_i32 s2, s2, 0x4800000
	s_mul_i32 s1, s14, 0x1200
	s_add_i32 s2, s2, s1
	s_add_i32 s2, s2, 0xcd00000
	s_add_u32 s86, s42, s2
	s_addc_u32 s87, s43, 0
	s_lshl_b32 s1, s56, 7
	s_lshr_b32 s2, s56, 2
	s_lshl_b32 s2, s2, 7
	s_cmp_eq_u32 s3, 1
	s_cselect_b32 s0, s2, s1
	s_mul_i32 s2, s3, 0x600
	s_sub_i32 s2, 0xa00, s2
	s_add_i32 s2, s2, s0
	s_add_u32 s24, s86, s2
	s_addc_u32 s25, s87, 0
	s_mul_i32 s2, s3, 0x900
	s_sub_i32 s2, 0xe00, s2
	s_add_i32 s2, s2, s0
	s_add_u32 s26, s86, s2
	s_addc_u32 s27, s87, 0
	s_mul_i32 s2, s3, 0x600
	s_sub_i32 s2, 0x600, s2
	s_add_i32 s2, s2, s1
	s_lshl_b32 s0, 0x12000, s13
	s_mul_i32 s0, s12, s0
	s_add_i32 s2, s2, s0
	s_add_u32 s62, s86, s2
	s_addc_u32 s63, s87, 0
	s_mov_b32 s10, 0
	s_mov_b32 s15, 0
	v_lshlrev_b32_e32 v100, s13, v116
	v_mul_u32_u24_e32 v100, 0x1200, v100
	v_lshl_add_u32 v111, v118, 1, v100
	v_and_b32_e32 v100, 63, v208
	v_and_b32_e32 v102, 7, v100
	v_lshlrev_b32_e32 v102, 4, v102
	v_lshrrev_b32_e32 v100, 3, v100
	v_add_u32_e32 v101, 0, v100
	v_lshlrev_b32_e32 v101, s13, v101
	v_mul_u32_u24_e32 v101, 0x1200, v101
	v_add_u32_e32 v112, v101, v102
	v_add_u32_e32 v101, 8, v100
	v_lshlrev_b32_e32 v101, s13, v101
	v_mul_u32_u24_e32 v101, 0x1200, v101
	v_add_u32_e32 v113, v101, v102
	global_load_dwordx4 v[16:19], v111, s[62:63]
	global_load_dwordx4 v[20:23], v111, s[62:63] offset:64
	s_lshl_b32 s1, 0x12000, s13
	s_mul_i32 s0, s11, s1
	s_add_u32 s16, s24, s0
	s_addc_u32 s17, s25, 0
	s_add_u32 s20, s26, s0
	s_addc_u32 s21, s27, 0
	s_add_i32 s2, s11, 1
	s_cmp_gt_i32 s2, s12
	s_cselect_b32 s2, s11, s2
	s_mul_i32 s0, s2, s1
	s_add_u32 s18, s24, s0
	s_addc_u32 s19, s25, 0
	s_add_u32 s22, s26, s0
	s_addc_u32 s23, s27, 0
	global_load_dwordx4 v[24:27], v111, s[16:17]
	global_load_dwordx4 v[28:31], v111, s[16:17] offset:64
	global_load_dwordx4 v[32:35], v111, s[18:19]
	global_load_dwordx4 v[36:39], v111, s[18:19] offset:64
	global_load_dwordx4 v[40:43], v112, s[20:21]
	global_load_dwordx4 v[44:47], v113, s[20:21]
	global_load_dwordx4 v[48:51], v112, s[22:23]
	global_load_dwordx4 v[52:55], v113, s[22:23]
	s_lshr_b32 s0, s6, 3
	s_cmp_eq_u32 s0, 0
	s_cselect_b32 s2, 1, 0
	s_cselect_b32 s3, 0, 8
	s_sub_i32 s2, 0x80, s2
	s_add_i32 s3, s3, s56
	v_and_b32_e32 v100, 63, v208
	v_lshlrev_b32_e32 v107, 2, v100
	v_add_u32_e32 v107, s48, v107
	v_add_u32_e32 v100, 0xffffffe0, v100
	v_mov_b32_e32 v106, 0xf149f2ca
	s_mov_b32 s0, 4
.Lb_lute:
	v_max_i32_e32 v101, 0, v100
	v_min_i32_e32 v101, 0xff, v101
	v_lshlrev_b32_e32 v101, s13, v101
	v_cvt_f32_u32_e32 v102, v101
	v_mul_f32_e32 v102, 0x3d800000, v102
	v_log_f32_e32 v102, v102
	s_nop 0
	v_mul_f32_e32 v102, 0x40124925, v102
	v_cvt_i32_f32_e32 v102, v102
	v_med3_i32 v102, v102, 0, 15
	v_add_u32_e32 v102, 16, v102
	v_cmp_gt_u32_e32 vcc, 16, v101
	s_nop 1
	v_cndmask_b32_e32 v102, v102, v101, vcc
	v_lshl_add_u32 v102, v102, 4, s3
	v_lshl_add_u32 v102, v102, 2, s57
	ds_read_b32 v102, v102
	v_cmp_ge_u32_e32 vcc, s2, v100
	s_waitcnt lgkmcnt(0)
	v_mul_f32_e32 v102, 0x3fb8aa3b, v102
	v_cndmask_b32_e32 v102, v106, v102, vcc
	ds_write_b32 v107, v102
	v_add_u32_e32 v100, 64, v100
	v_add_u32_e32 v107, 0x100, v107
	s_add_i32 s0, s0, -1
	s_cmp_lg_u32 s0, 0
	s_cbranch_scc1 .Lb_lute
	s_waitcnt lgkmcnt(0)
	s_lshl_b32 s0, s11, 4
	s_sub_i32 s0, s8, s0
	s_add_i32 s0, s0, 13
	s_lshl_b32 s0, s0, 2
	s_add_i32 s0, s0, s48
	v_sub_u32_e32 v110, v116, v117
	v_lshl_add_u32 v110, v110, 2, s0
	s_lshr_b32 s0, s6, 3
	s_cmp_eq_u32 s0, 0
	s_cselect_b64 vcc, -1, 0
	v_mov_b32_e32 v100, 0xefa18f08
	s_nop 1
	v_cndmask_b32_e32 v108, v100, v119, vcc
	v_cndmask_b32_e32 v109, 0, v120, vcc
	v_mov_b32_e32 v0, 0
	v_mov_b32_e32 v1, 0
	v_mov_b32_e32 v2, 0
	v_mov_b32_e32 v3, 0
	v_mov_b32_e32 v4, 0
	v_mov_b32_e32 v5, 0
	v_mov_b32_e32 v6, 0
	v_mov_b32_e32 v7, 0
	v_mov_b32_e32 v8, 0
	v_mov_b32_e32 v9, 0
	v_mov_b32_e32 v10, 0
	v_mov_b32_e32 v11, 0
	v_mov_b32_e32 v12, 0
	v_mov_b32_e32 v13, 0
	v_mov_b32_e32 v14, 0
	v_mov_b32_e32 v15, 0
.Lb_step:
	s_waitcnt vmcnt(0)
	ds_write_b128 v114, v[40:43] offset:0
	ds_write_b128 v114, v[44:47] offset:1152
	ds_write_b128 v114, v[48:51] offset:2304
	ds_write_b128 v114, v[52:55] offset:3456
	ds_read_b32 v100, v110 offset:76
	ds_read_b32 v101, v110 offset:72
	ds_read_b32 v102, v110 offset:68
	ds_read_b32 v103, v110 offset:64
	ds_read_b32 v104, v110 offset:12
	ds_read_b32 v105, v110 offset:8
	ds_read_b32 v106, v110 offset:4
	ds_read_b32 v107, v110 offset:0
	v_add_u32_e32 v110, 0xffffff80, v110
	v_mfma_f32_16x16x32_bf16 v[92:95], v[24:27], v[16:19], 0
	v_mfma_f32_16x16x32_bf16 v[96:99], v[32:35], v[16:19], 0
	v_mfma_f32_16x16x32_bf16 v[92:95], v[28:31], v[20:23], v[92:95]
	v_mfma_f32_16x16x32_bf16 v[96:99], v[36:39], v[20:23], v[96:99]
	s_add_i32 s1, s10, 1
	s_cmp_ge_i32 s1, s9
	s_cbranch_scc1 .Lb_last
	s_mov_b32 s49, 0
	s_add_i32 s3, s11, 2
	s_lshl_b32 s1, 0x12000, s13
	s_mul_i32 s0, s3, s1
	s_add_u32 s16, s24, s0
	s_addc_u32 s17, s25, 0
	s_add_u32 s20, s26, s0
	s_addc_u32 s21, s27, 0
	s_add_i32 s2, s3, 1
	s_cmp_gt_i32 s2, s12
	s_cselect_b32 s2, s3, s2
	s_mul_i32 s0, s2, s1
	s_add_u32 s18, s24, s0
	s_addc_u32 s19, s25, 0
	s_add_u32 s22, s26, s0
	s_addc_u32 s23, s27, 0
	global_load_dwordx4 v[24:27], v111, s[16:17]
	global_load_dwordx4 v[28:31], v111, s[16:17] offset:64
	global_load_dwordx4 v[32:35], v111, s[18:19]
	global_load_dwordx4 v[36:39], v111, s[18:19] offset:64
	global_load_dwordx4 v[40:43], v112, s[20:21]
	global_load_dwordx4 v[44:47], v113, s[20:21]
	global_load_dwordx4 v[48:51], v112, s[22:23]
	global_load_dwordx4 v[52:55], v113, s[22:23]
	s_branch .Lb_compute
.Lb_last:
	s_mov_b32 s49, 1
	s_add_i32 s0, s6, 1
	s_min_i32 s0, s0, 31
	s_mov_b32 s15, s0
	s_lshr_b32 s0, s15, 3
	s_cmp_eq_u32 s0, 0
	s_cselect_b32 s3, 1, 0
	s_add_i32 s1, s0, -1
	s_max_i32 s1, s1, 0
	s_lshl_b32 s38, s1, 1
	s_and_b32 s1, s15, 3
	s_lshl_b32 s1, s1, 8
	s_add_i32 s1, s1, s7
	s_sub_i32 s2, 10, s38
	s_lshr_b32 s39, s1, s2
	s_lshr_b32 s2, 0x400, s38
	s_add_i32 s2, s2, -1
	s_and_b32 s37, s1, s2
	s_lshl_b32 s34, s37, 4
	s_sub_i32 s2, 0x80, s3
	s_sub_i32 s2, s34, s2
	s_max_i32 s2, s2, 0
	s_lshr_b32 s2, s2, 4
	s_and_b32 s36, s2, -2
	s_sub_i32 s2, s37, s36
	s_lshr_b32 s2, s2, 1
	s_add_i32 s35, s2, 1
	s_bfe_u32 s2, s15, 0x10002
	s_mul_i32 s2, s2, 0x4800000
	s_mul_i32 s1, s39, 0x1200
	s_add_i32 s2, s2, s1
	s_add_i32 s2, s2, 0xcd00000
	s_add_u32 s86, s42, s2
	s_addc_u32 s87, s43, 0
	s_lshl_b32 s1, s56, 7
	s_lshr_b32 s2, s56, 2
	s_lshl_b32 s2, s2, 7
	s_cmp_eq_u32 s3, 1
	s_cselect_b32 s0, s2, s1
	s_mul_i32 s2, s3, 0x600
	s_sub_i32 s2, 0xa00, s2
	s_add_i32 s2, s2, s0
	s_add_u32 s24, s86, s2
	s_addc_u32 s25, s87, 0
	s_mul_i32 s2, s3, 0x900
	s_sub_i32 s2, 0xe00, s2
	s_add_i32 s2, s2, s0
	s_add_u32 s26, s86, s2
	s_addc_u32 s27, s87, 0
	s_mul_i32 s2, s3, 0x600
	s_sub_i32 s2, 0x600, s2
	s_add_i32 s2, s2, s1
	s_lshl_b32 s0, 0x12000, s38
	s_mul_i32 s0, s37, s0
	s_add_i32 s2, s2, s0
	s_add_u32 s62, s86, s2
	s_addc_u32 s63, s87, 0
	s_waitcnt lgkmcnt(0)
	v_pk_fma_f32 v[92:93], v[92:93], s[40:41], v[100:101] op_sel_hi:[1,0,1]
	v_pk_fma_f32 v[94:95], v[94:95], s[40:41], v[102:103] op_sel_hi:[1,0,1]
	v_pk_fma_f32 v[96:97], v[96:97], s[40:41], v[104:105] op_sel_hi:[1,0,1]
	v_pk_fma_f32 v[98:99], v[98:99], s[40:41], v[106:107] op_sel_hi:[1,0,1]
	v_lshlrev_b32_e32 v100, s38, v116
	v_mul_u32_u24_e32 v100, 0x1200, v100
	v_lshl_add_u32 v111, v118, 1, v100
	v_and_b32_e32 v100, 63, v208
	v_and_b32_e32 v102, 7, v100
	v_lshlrev_b32_e32 v102, 4, v102
	v_lshrrev_b32_e32 v100, 3, v100
	v_add_u32_e32 v101, 0, v100
	v_lshlrev_b32_e32 v101, s38, v101
	v_mul_u32_u24_e32 v101, 0x1200, v101
	v_add_u32_e32 v112, v101, v102
	v_add_u32_e32 v101, 8, v100
	v_lshlrev_b32_e32 v101, s38, v101
	v_mul_u32_u24_e32 v101, 0x1200, v101
	v_add_u32_e32 v113, v101, v102
	s_lshl_b32 s1, 0x12000, s38
	s_mul_i32 s0, s36, s1
	s_add_u32 s16, s24, s0
	s_addc_u32 s17, s25, 0
	s_add_u32 s20, s26, s0
	s_addc_u32 s21, s27, 0
	s_add_i32 s2, s36, 1
	s_cmp_gt_i32 s2, s37
	s_cselect_b32 s2, s36, s2
	s_mul_i32 s0, s2, s1
	s_add_u32 s18, s24, s0
	s_addc_u32 s19, s25, 0
	s_add_u32 s22, s26, s0
	s_addc_u32 s23, s27, 0
	global_load_dwordx4 v[24:27], v111, s[16:17]
	global_load_dwordx4 v[28:31], v111, s[16:17] offset:64
	global_load_dwordx4 v[32:35], v111, s[18:19]
	global_load_dwordx4 v[36:39], v111, s[18:19] offset:64
	global_load_dwordx4 v[40:43], v112, s[20:21]
	global_load_dwordx4 v[44:47], v113, s[20:21]
	global_load_dwordx4 v[48:51], v112, s[22:23]
	global_load_dwordx4 v[52:55], v113, s[22:23]
	global_load_dwordx4 v[16:19], v111, s[62:63]
	global_load_dwordx4 v[20:23], v111, s[62:63] offset:64
	ds_read_u16 v56, v115 offset:0
	ds_read_u16 v74, v115 offset:144
	ds_read_u16 v57, v115 offset:288
	ds_read_u16 v75, v115 offset:432
	ds_read_u16 v60, v115 offset:32
	ds_read_u16 v78, v115 offset:176
	ds_read_u16 v61, v115 offset:320
	ds_read_u16 v79, v115 offset:464
	ds_read_u16 v66, v115 offset:64
	ds_read_u16 v82, v115 offset:208
	ds_read_u16 v67, v115 offset:352
	ds_read_u16 v83, v115 offset:496
	ds_read_u16 v70, v115 offset:96
	ds_read_u16 v86, v115 offset:240
	ds_read_u16 v71, v115 offset:384
	ds_read_u16 v87, v115 offset:528
	ds_read_u16 v58, v115 offset:2304
	ds_read_u16 v76, v115 offset:2448
	ds_read_u16 v59, v115 offset:2592
	ds_read_u16 v77, v115 offset:2736
	ds_read_u16 v62, v115 offset:2336
	ds_read_u16 v80, v115 offset:2480
	ds_read_u16 v63, v115 offset:2624
	ds_read_u16 v81, v115 offset:2768
	ds_read_u16 v68, v115 offset:2368
	ds_read_u16 v84, v115 offset:2512
	ds_read_u16 v69, v115 offset:2656
	ds_read_u16 v85, v115 offset:2800
	ds_read_u16 v72, v115 offset:2400
	ds_read_u16 v88, v115 offset:2544
	ds_read_u16 v73, v115 offset:2688
	ds_read_u16 v89, v115 offset:2832
	s_branch .Lb_softmax
.Lb_compute:
	s_waitcnt lgkmcnt(0)
	ds_read_u16 v56, v115 offset:0
	ds_read_u16 v74, v115 offset:144
	ds_read_u16 v57, v115 offset:288
	ds_read_u16 v75, v115 offset:432
	ds_read_u16 v60, v115 offset:32
	ds_read_u16 v78, v115 offset:176
	ds_read_u16 v61, v115 offset:320
	ds_read_u16 v79, v115 offset:464
	ds_read_u16 v66, v115 offset:64
	ds_read_u16 v82, v115 offset:208
	ds_read_u16 v67, v115 offset:352
	ds_read_u16 v83, v115 offset:496
	ds_read_u16 v70, v115 offset:96
	ds_read_u16 v86, v115 offset:240
	ds_read_u16 v71, v115 offset:384
	ds_read_u16 v87, v115 offset:528
	ds_read_u16 v58, v115 offset:2304
	ds_read_u16 v76, v115 offset:2448
	ds_read_u16 v59, v115 offset:2592
	ds_read_u16 v77, v115 offset:2736
	ds_read_u16 v62, v115 offset:2336
	ds_read_u16 v80, v115 offset:2480
	ds_read_u16 v63, v115 offset:2624
	ds_read_u16 v81, v115 offset:2768
	ds_read_u16 v68, v115 offset:2368
	ds_read_u16 v84, v115 offset:2512
	ds_read_u16 v69, v115 offset:2656
	ds_read_u16 v85, v115 offset:2800
	ds_read_u16 v72, v115 offset:2400
	ds_read_u16 v88, v115 offset:2544
	ds_read_u16 v73, v115 offset:2688
	ds_read_u16 v89, v115 offset:2832
	v_pk_fma_f32 v[92:93], v[92:93], s[40:41], v[100:101] op_sel_hi:[1,0,1]
	v_pk_fma_f32 v[94:95], v[94:95], s[40:41], v[102:103] op_sel_hi:[1,0,1]
	v_pk_fma_f32 v[96:97], v[96:97], s[40:41], v[104:105] op_sel_hi:[1,0,1]
	v_pk_fma_f32 v[98:99], v[98:99], s[40:41], v[106:107] op_sel_hi:[1,0,1]
.Lb_softmax:
	v_max3_f32 v100, v92, v93, v94
	v_max3_f32 v101, v95, v96, v97
	v_max3_f32 v100, v100, v98, v99
	v_max_f32_e32 v100, v100, v101
	v_mov_b32_e32 v101, v100
	s_nop 1
	v_permlane16_swap_b32_e32 v101, v100
	v_max_f32_e32 v100, v100, v101
	v_mov_b32_e32 v101, v100
	s_nop 1
	v_permlane32_swap_b32_e32 v101, v100
	v_max_f32_e32 v102, v100, v101
	v_cmp_gt_f32_e32 vcc, v102, v108
	s_cbranch_vccz .Lb_noresc
	v_max_f32_e32 v102, v108, v102
	v_sub_f32_e32 v100, v108, v102
	v_exp_f32_e32 v100, v100
	v_mov_b32_e32 v108, v102
	s_nop 0
	v_pk_mul_f32 v[0:1], v[0:1], v[100:101] op_sel_hi:[1,0]
	v_pk_mul_f32 v[2:3], v[2:3], v[100:101] op_sel_hi:[1,0]
	v_pk_mul_f32 v[4:5], v[4:5], v[100:101] op_sel_hi:[1,0]
	v_pk_mul_f32 v[6:7], v[6:7], v[100:101] op_sel_hi:[1,0]
	v_pk_mul_f32 v[8:9], v[8:9], v[100:101] op_sel_hi:[1,0]
	v_pk_mul_f32 v[10:11], v[10:11], v[100:101] op_sel_hi:[1,0]
	v_pk_mul_f32 v[12:13], v[12:13], v[100:101] op_sel_hi:[1,0]
	v_pk_mul_f32 v[14:15], v[14:15], v[100:101] op_sel_hi:[1,0]
	v_mul_f32_e32 v109, v109, v100
.Lb_noresc:
	v_pk_add_f32 v[92:93], v[92:93], v[108:109] op_sel_hi:[1,0] neg_lo:[0,1] neg_hi:[0,1]
	v_pk_add_f32 v[94:95], v[94:95], v[108:109] op_sel_hi:[1,0] neg_lo:[0,1] neg_hi:[0,1]
	v_pk_add_f32 v[96:97], v[96:97], v[108:109] op_sel_hi:[1,0] neg_lo:[0,1] neg_hi:[0,1]
	v_pk_add_f32 v[98:99], v[98:99], v[108:109] op_sel_hi:[1,0] neg_lo:[0,1] neg_hi:[0,1]
	v_exp_f32_e32 v92, v92
	v_exp_f32_e32 v93, v93
	v_exp_f32_e32 v94, v94
	v_exp_f32_e32 v95, v95
	v_exp_f32_e32 v96, v96
	v_exp_f32_e32 v97, v97
	v_exp_f32_e32 v98, v98
	v_exp_f32_e32 v99, v99
	s_nop 0
	v_pk_add_f32 v[100:101], v[92:93], v[94:95]
	v_pk_add_f32 v[100:101], v[100:101], v[96:97]
	v_pk_add_f32 v[100:101], v[100:101], v[98:99]
	v_add_f32_e32 v100, v100, v101
	v_add_f32_e32 v109, v109, v100
	v_cvt_pk_bf16_f32 v92, v92, v93
	v_cvt_pk_bf16_f32 v93, v94, v95
	v_cvt_pk_bf16_f32 v94, v96, v97
	v_cvt_pk_bf16_f32 v95, v98, v99
	s_waitcnt lgkmcnt(0)
	v_lshl_or_b32 v56, v74, 16, v56
	v_lshl_or_b32 v57, v75, 16, v57
	v_lshl_or_b32 v58, v76, 16, v58
	v_lshl_or_b32 v59, v77, 16, v59
	v_lshl_or_b32 v60, v78, 16, v60
	v_lshl_or_b32 v61, v79, 16, v61
	v_lshl_or_b32 v62, v80, 16, v62
	v_lshl_or_b32 v63, v81, 16, v63
	v_lshl_or_b32 v66, v82, 16, v66
	v_lshl_or_b32 v67, v83, 16, v67
	v_lshl_or_b32 v68, v84, 16, v68
	v_lshl_or_b32 v69, v85, 16, v69
	v_lshl_or_b32 v70, v86, 16, v70
	v_lshl_or_b32 v71, v87, 16, v71
	v_lshl_or_b32 v72, v88, 16, v72
	v_lshl_or_b32 v73, v89, 16, v73
	s_nop 1
	v_mfma_f32_16x16x32_bf16 v[0:3], v[56:59], v[92:95], v[0:3]
	v_mfma_f32_16x16x32_bf16 v[4:7], v[60:63], v[92:95], v[4:7]
	v_mfma_f32_16x16x32_bf16 v[8:11], v[66:69], v[92:95], v[8:11]
	v_mfma_f32_16x16x32_bf16 v[12:15], v[70:73], v[92:95], v[12:15]
	s_cmp_eq_u32 s49, 0
	s_cbranch_scc0 .Lb_epilogue
	s_add_i32 s10, s10, 1
	s_add_i32 s11, s11, 2
	s_branch .Lb_step
.Lb_epilogue:
	s_nop 7
	v_mov_b32_e32 v100, v109
	s_nop 1
	v_permlane16_swap_b32_e32 v100, v109
	v_add_f32_e32 v109, v109, v100
	v_mov_b32_e32 v100, v109
	s_nop 1
	v_permlane32_swap_b32_e32 v100, v109
	v_add_f32_e32 v109, v109, v100
	v_rcp_f32_e32 v102, v109
	v_log_f32_e32 v103, v109
	s_nop 0
	v_pk_mul_f32 v[0:1], v[0:1], v[102:103] op_sel_hi:[1,0]
	v_pk_mul_f32 v[2:3], v[2:3], v[102:103] op_sel_hi:[1,0]
	v_pk_mul_f32 v[4:5], v[4:5], v[102:103] op_sel_hi:[1,0]
	v_pk_mul_f32 v[6:7], v[6:7], v[102:103] op_sel_hi:[1,0]
	v_pk_mul_f32 v[8:9], v[8:9], v[102:103] op_sel_hi:[1,0]
	v_pk_mul_f32 v[10:11], v[10:11], v[102:103] op_sel_hi:[1,0]
	v_pk_mul_f32 v[12:13], v[12:13], v[102:103] op_sel_hi:[1,0]
	v_pk_mul_f32 v[14:15], v[14:15], v[102:103] op_sel_hi:[1,0]
	v_add_f32_e32 v103, v103, v108
	v_mul_f32_e32 v103, 0x3f317218, v103
	s_lshl_b32 s0, s8, s13
	s_add_i32 s0, s0, s14
	s_lshr_b32 s1, s6, 3
	s_bfe_u32 s2, s6, 0x10002
	s_cmp_eq_u32 s1, 0
	s_cbranch_scc1 .Lb_ep_mixer
	s_add_i32 s1, s1, -1
	s_lshl_b32 s1, s1, 15
	s_lshl_b32 s2, s2, 14
	s_add_i32 s1, s1, s2
	s_add_i32 s1, s1, s0
	s_lshl_b32 s2, s1, 5
	s_lshl_b32 s3, s56, 2
	s_add_i32 s2, s2, s3
	s_add_i32 s2, s2, 0x1bd00000
	s_add_u32 s86, s42, s2
	s_addc_u32 s87, s43, 0
	v_lshlrev_b32_e32 v104, s13, v116
	v_lshlrev_b32_e32 v122, 5, v104
	s_mov_b64 exec, 0xffff
	global_store_dword v122, v103, s[86:87]
	s_mov_b64 exec, -1
	s_lshl_b32 s2, s1, 10
	s_lshl_b32 s3, s56, 7
	s_add_i32 s2, s2, s3
	s_add_i32 s2, s2, 0x15d00000
	s_add_u32 s86, s42, s2
	s_addc_u32 s87, s43, 0
	v_lshl_add_u32 v121, v104, 10, v118
	s_branch .Lb_ep_store
.Lb_ep_mixer:
	s_lshl_b32 s2, s2, 14
	s_add_i32 s1, s2, s0
	s_lshl_b32 s2, s1, 11
	s_lshl_b32 s3, s56, 7
	s_add_i32 s2, s2, s3
	s_add_i32 s2, s2, 0x6d00000
	s_add_u32 s86, s42, s2
	s_addc_u32 s87, s43, 0
	v_lshl_add_u32 v121, v116, 11, v118
.Lb_ep_store:
	v_cvt_pk_bf16_f32 v0, v0, v1
	v_cvt_pk_bf16_f32 v1, v2, v3
	global_store_dwordx2 v121, v[0:1], s[86:87] offset:0
	v_cvt_pk_bf16_f32 v4, v4, v5
	v_cvt_pk_bf16_f32 v5, v6, v7
	global_store_dwordx2 v121, v[4:5], s[86:87] offset:32
	v_cvt_pk_bf16_f32 v8, v8, v9
	v_cvt_pk_bf16_f32 v9, v10, v11
	global_store_dwordx2 v121, v[8:9], s[86:87] offset:64
	v_cvt_pk_bf16_f32 v12, v12, v13
	v_cvt_pk_bf16_f32 v13, v14, v15
	global_store_dwordx2 v121, v[12:13], s[86:87] offset:96
	s_add_i32 s0, s6, 1
	s_cmp_ge_i32 s0, 32
	s_cbranch_scc1 .Lb_exit
	s_lshr_b32 s1, s6, 3
	s_mov_b32 s6, s0
	s_mov_b32 s8, s34
	s_mov_b32 s9, s35
	s_mov_b32 s11, s36
	s_mov_b32 s12, s37
	s_mov_b32 s13, s38
	s_mov_b32 s14, s39
	s_mov_b32 s10, 0
	s_lshr_b32 s0, s6, 3
	s_cmp_eq_u32 s0, s1
	s_cbranch_scc1 .Lb_samekind
	s_lshr_b32 s0, s6, 3
	s_cmp_eq_u32 s0, 0
	s_cselect_b32 s2, 1, 0
	s_cselect_b32 s3, 0, 8
	s_sub_i32 s2, 0x80, s2
	s_add_i32 s3, s3, s56
	v_and_b32_e32 v100, 63, v208
	v_lshlrev_b32_e32 v107, 2, v100
	v_add_u32_e32 v107, s48, v107
	v_add_u32_e32 v100, 0xffffffe0, v100
	v_mov_b32_e32 v106, 0xf149f2ca
	s_mov_b32 s0, 4
.Lb_lutn:
	v_max_i32_e32 v101, 0, v100
	v_min_i32_e32 v101, 0xff, v101
	v_lshlrev_b32_e32 v101, s13, v101
	v_cvt_f32_u32_e32 v102, v101
	v_mul_f32_e32 v102, 0x3d800000, v102
	v_log_f32_e32 v102, v102
	s_nop 0
	v_mul_f32_e32 v102, 0x40124925, v102
	v_cvt_i32_f32_e32 v102, v102
	v_med3_i32 v102, v102, 0, 15
	v_add_u32_e32 v102, 16, v102
	v_cmp_gt_u32_e32 vcc, 16, v101
	s_nop 1
	v_cndmask_b32_e32 v102, v102, v101, vcc
	v_lshl_add_u32 v102, v102, 4, s3
	v_lshl_add_u32 v102, v102, 2, s57
	ds_read_b32 v102, v102
	v_cmp_ge_u32_e32 vcc, s2, v100
	s_waitcnt lgkmcnt(0)
	v_mul_f32_e32 v102, 0x3fb8aa3b, v102
	v_cndmask_b32_e32 v102, v106, v102, vcc
	ds_write_b32 v107, v102
	v_add_u32_e32 v100, 64, v100
	v_add_u32_e32 v107, 0x100, v107
	s_add_i32 s0, s0, -1
	s_cmp_lg_u32 s0, 0
	s_cbranch_scc1 .Lb_lutn
	s_waitcnt lgkmcnt(0)
.Lb_samekind:
	s_lshl_b32 s0, s11, 4
	s_sub_i32 s0, s8, s0
	s_add_i32 s0, s0, 13
	s_lshl_b32 s0, s0, 2
	s_add_i32 s0, s0, s48
	v_sub_u32_e32 v110, v116, v117
	v_lshl_add_u32 v110, v110, 2, s0
	s_lshr_b32 s0, s6, 3
	s_cmp_eq_u32 s0, 0
	s_cselect_b64 vcc, -1, 0
	v_mov_b32_e32 v100, 0xefa18f08
	s_nop 1
	v_cndmask_b32_e32 v108, v100, v119, vcc
	v_cndmask_b32_e32 v109, 0, v120, vcc
	v_mov_b32_e32 v0, 0
	v_mov_b32_e32 v1, 0
	v_mov_b32_e32 v2, 0
	v_mov_b32_e32 v3, 0
	v_mov_b32_e32 v4, 0
	v_mov_b32_e32 v5, 0
	v_mov_b32_e32 v6, 0
	v_mov_b32_e32 v7, 0
	v_mov_b32_e32 v8, 0
	v_mov_b32_e32 v9, 0
	v_mov_b32_e32 v10, 0
	v_mov_b32_e32 v11, 0
	v_mov_b32_e32 v12, 0
	v_mov_b32_e32 v13, 0
	v_mov_b32_e32 v14, 0
	v_mov_b32_e32 v15, 0
	s_branch .Lb_step

.Lband_orig:
	s_add_u32 s36, s0, 0xcd00000
	s_addc_u32 s37, s1, 0
	s_add_u32 s38, s0, 0x6d00000
	s_addc_u32 s39, s1, 0
	s_load_dwordx2 s[34:35], s[2:3], 0x30
	v_and_b32_e32 v1, 63, v0
	s_add_u32 s40, s0, 0x15d00000
	v_bfe_u32 v2, v0, 4, 2
	s_addc_u32 s41, s1, 0
	v_and_b32_e32 v48, 15, v0
	v_lshlrev_b32_e32 v52, 2, v2
	v_lshlrev_b32_e32 v0, 2, v1
	s_add_u32 s62, s0, 0x1bd00000
	v_xor_b32_e32 v51, 64, v0
	v_xor_b32_e32 v53, 0x80, v0
	v_sub_u32_e32 v0, v48, v52
	v_lshlrev_b32_e32 v64, 1, v48
	s_addc_u32 s63, s1, 0
	v_cmp_gt_u32_e64 s[8:9], 16, v1
	v_readlane_b32 s2, v254, 33
	v_subrev_u32_e32 v69, 19, v0
	v_lshl_add_u64 v[0:1], s[0:1], 0, v[64:65]
	s_mov_b64 s[0:1], 0xcd00500
	v_lshlrev_b32_e32 v50, 3, v2
	v_cndmask_b32_e64 v68, 0, 1.0, s[8:9]
	s_lshl_b32 s6, s2, 3
	v_or_b32_e32 v70, 3, v52
	v_lshl_add_u64 v[54:55], v[0:1], 0, s[0:1]
	s_mov_b64 s[86:87], 0
	v_mov_b32_e32 v71, v49
	v_readlane_b32 s3, v254, 34
	s_branch .LBB0_1167
